# P4 rstd-table build: fast path (256 workgroups, 12 rounds) with all 6 rounds' stats loads issued up front instead of 6 dependent load-reduce rounds, on top of P1 LDS tables + P2 pointer SALU
# speedup vs baseline: 1.0062x; 1.0036x over previous
;     __device__ __forceinline__ int pm_at(int i) const {
;         if (i >= R) return -1;
;         const long L = (long)(rev ? R - 1 - i : i) * G + c; if (L >= nwg) return -1;
;         int wgid = (int)L; { const int q = nwg / NXCD, r = nwg % NXCD, xcd = wgid % NXCD, off = wgid / NXCD; wgid = (xcd < r ? xcd * (q + 1) : r * (q + 1) + (xcd - r) * q) + off; }
;         const int nig = WGM * nN, gid = wgid / nig, fm = gid * WGM, gsz = (nM - fm) < WGM ? (nM - fm) : WGM;
;         return fm + ((wgid % nig) % gsz);
;     }
; __global__ void __launch_bounds__(NWAVES * 64, 2) mega_fwd(Args args) {
;     ...
;         { const int rowi = F.tid & 255;
;           for (int i = F.tid >> 8; i < pg8::UP_TAB_ROUNDS; i += 2) { const int pm = S.pm_at(i); if (pm < 0) break;
;               const f32x4* p = (const f32x4*)(F.stats + (size_t)(pm * 256 + rowi) * 16); const f32x4 a = p[0], b = p[1], c = p[2], d = p[3];
;               const float ssum = ((a[0] + a[1]) + (a[2] + a[3])) + ((b[0] + b[1]) + (b[2] + b[3])) + ((c[0] + c[1]) + (c[2] + c[3])) + ((d[0] + d[1]) + (d[2] + d[3]));
;               tab[i * 256 + rowi] = __builtin_amdgcn_rsqf(ssum * (1.0f / 1024.0f) + EPS); }
.LBB0_1358:
	s_cmp_lt_i32 s68, 5
	s_cselect_b64 s[0:1], -1, 0
	s_cmp_gt_u32 s33, 4
	s_cselect_b64 s[4:5], -1, 0
	s_and_b64 s[0:1], s[0:1], s[4:5]
	s_andn2_b64 vcc, exec, s[0:1]
	s_cbranch_vccnz .LBB0_1486
	s_abs_i32 s0, s42
	v_cvt_f32_u32_e32 v1, s0
	s_add_i32 s1, s42, 0xbff
	s_sub_i32 s3, 0xfffff401, s42
	s_xor_b32 s4, s1, s42
	v_rcp_iflag_f32_e32 v2, v1
	s_max_i32 s1, s1, s3
	s_sub_i32 s3, 0, s0
	s_ashr_i32 s4, s4, 31
	v_mul_f32_e32 v2, 0x4f7ffffe, v2
	v_cvt_u32_f32_e32 v2, v2
	v_and_b32_e32 v1, 0xff, v208
	v_lshrrev_b32_e32 v6, 8, v208
	v_lshlrev_b32_e32 v4, 2, v1
	v_readfirstlane_b32 s5, v2
	s_mul_i32 s3, s3, s5
	s_mul_hi_u32 s3, s5, s3
	s_add_i32 s5, s5, s3
	s_mul_hi_u32 s3, s1, s5
	s_mul_i32 s5, s3, s0
	s_sub_i32 s1, s1, s5
	s_add_i32 s6, s3, 1
	s_sub_i32 s5, s1, s0
	s_cmp_ge_u32 s1, s0
	s_cselect_b32 s3, s6, s3
	s_cselect_b32 s1, s5, s1
	s_add_i32 s5, s3, 1
	s_cmp_ge_u32 s1, s0
	s_cselect_b32 s0, s5, s3
	s_ashr_i32 s3, s2, 31
	v_lshl_or_b32 v4, v6, 10, v4
	s_xor_b32 s0, s0, s4
	s_ashr_i32 s43, s42, 31
	s_waitcnt lgkmcnt(0)
	v_mov_b64_e32 v[2:3], s[2:3]
	v_add_u32_e32 v4, 0x100, v4
	s_sub_i32 s30, s0, s4
	v_mad_i64_i32 v[2:3], s[0:1], v6, s42, v[2:3]
	s_lshl_b64 s[4:5], s[42:43], 1
	v_add_u32_e32 v7, 0x20800, v4
	s_mov_b64 s[6:7], 0
	s_mov_b64 s[10:11], 0xc00
	v_mov_b32_e32 v5, 0
	s_waitcnt vmcnt(0)
	v_mov_b32_e32 v8, 0x358637bd
	v_mov_b32_e32 v9, 0x180
	v_mov_b32_e32 v10, 0x181
	s_cmp_eq_u32 s30, 12
	s_cbranch_scc0 .Ltab_slow
	s_cmpk_eq_i32 s42, 0x100
	s_cbranch_scc0 .Ltab_slow
	v_ashrrev_i32_e32 v4, 31, v2
	v_lshrrev_b32_e32 v4, 29, v4
	v_add_u32_e32 v4, v2, v4
	v_ashrrev_i32_e32 v11, 3, v4
	v_and_b32_e32 v4, -8, v4
	v_sub_u32_e32 v4, v2, v4
	v_cmp_gt_i32_e32 vcc, 0, v4
	s_nop 1
	v_cndmask_b32_e32 v12, v9, v10, vcc
	v_mul_lo_u32 v4, v4, v12
	v_add_u32_e32 v4, v4, v11
	v_ashrrev_i32_e32 v11, 31, v4
	v_lshrrev_b32_e32 v11, 25, v11
	v_add_u32_e32 v11, v4, v11
	v_ashrrev_i32_e32 v12, 7, v11
	v_lshlrev_b32_e32 v12, 3, v12
	v_sub_u32_e32 v13, 0xc0, v12
	v_min_i32_e32 v13, 8, v13
	v_sub_u32_e32 v14, 0, v13
	v_max_i32_e32 v13, v13, v14
	v_cvt_f32_u32_e32 v14, v13
	v_and_b32_e32 v11, 0xffffff80, v11
	v_sub_u32_e32 v4, v4, v11
	v_sub_u32_e32 v15, 0, v4
	v_rcp_iflag_f32_e32 v14, v14
	v_ashrrev_i32_e32 v11, 31, v4
	v_max_i32_e32 v4, v4, v15
	v_sub_u32_e32 v15, 0, v13
	v_mul_f32_e32 v14, 0x4f7ffffe, v14
	v_cvt_u32_f32_e32 v14, v14
	v_mul_lo_u32 v15, v15, v14
	v_mul_hi_u32 v15, v14, v15
	v_add_u32_e32 v14, v14, v15
	v_mul_hi_u32 v14, v4, v14
	v_mul_lo_u32 v14, v14, v13
	v_sub_u32_e32 v4, v4, v14
	v_sub_u32_e32 v14, v4, v13
	v_cmp_ge_u32_e32 vcc, v4, v13
	s_nop 1
	v_cndmask_b32_e32 v4, v4, v14, vcc
	v_sub_u32_e32 v14, v4, v13
	v_cmp_ge_u32_e32 vcc, v4, v13
	s_nop 1
	v_cndmask_b32_e32 v4, v4, v14, vcc
	v_xor_b32_e32 v4, v4, v11
	v_sub_u32_e32 v4, v4, v11
	v_add_u32_e32 v4, v12, v4
	v_lshl_or_b32 v4, v4, 8, v1
	v_lshlrev_b64 v[12:13], 6, v[4:5]
	v_lshl_add_u64 v[28:29], s[8:9], 0, v[12:13]
	global_load_dwordx4 v[32:35], v[28:29], off
	global_load_dwordx4 v[36:39], v[28:29], off offset:16
	global_load_dwordx4 v[40:43], v[28:29], off offset:32
	global_load_dwordx4 v[44:47], v[28:29], off offset:48
	v_lshl_add_u64 v[2:3], v[2:3], 0, s[4:5]
	v_ashrrev_i32_e32 v4, 31, v2
	v_lshrrev_b32_e32 v4, 29, v4
	v_add_u32_e32 v4, v2, v4
	v_ashrrev_i32_e32 v11, 3, v4
	v_and_b32_e32 v4, -8, v4
	v_sub_u32_e32 v4, v2, v4
	v_cmp_gt_i32_e32 vcc, 0, v4
	s_nop 1
	v_cndmask_b32_e32 v12, v9, v10, vcc
	v_mul_lo_u32 v4, v4, v12
	v_add_u32_e32 v4, v4, v11
	v_ashrrev_i32_e32 v11, 31, v4
	v_lshrrev_b32_e32 v11, 25, v11
	v_add_u32_e32 v11, v4, v11
	v_ashrrev_i32_e32 v12, 7, v11
	v_lshlrev_b32_e32 v12, 3, v12
	v_sub_u32_e32 v13, 0xc0, v12
	v_min_i32_e32 v13, 8, v13
	v_sub_u32_e32 v14, 0, v13
	v_max_i32_e32 v13, v13, v14
	v_cvt_f32_u32_e32 v14, v13
	v_and_b32_e32 v11, 0xffffff80, v11
	v_sub_u32_e32 v4, v4, v11
	v_sub_u32_e32 v15, 0, v4
	v_rcp_iflag_f32_e32 v14, v14
	v_ashrrev_i32_e32 v11, 31, v4
	v_max_i32_e32 v4, v4, v15
	v_sub_u32_e32 v15, 0, v13
	v_mul_f32_e32 v14, 0x4f7ffffe, v14
	v_cvt_u32_f32_e32 v14, v14
	v_mul_lo_u32 v15, v15, v14
	v_mul_hi_u32 v15, v14, v15
	v_add_u32_e32 v14, v14, v15
	v_mul_hi_u32 v14, v4, v14
	v_mul_lo_u32 v14, v14, v13
	v_sub_u32_e32 v4, v4, v14
	v_sub_u32_e32 v14, v4, v13
	v_cmp_ge_u32_e32 vcc, v4, v13
	s_nop 1
	v_cndmask_b32_e32 v4, v4, v14, vcc
	v_sub_u32_e32 v14, v4, v13
	v_cmp_ge_u32_e32 vcc, v4, v13
	s_nop 1
	v_cndmask_b32_e32 v4, v4, v14, vcc
	v_xor_b32_e32 v4, v4, v11
	v_sub_u32_e32 v4, v4, v11
	v_add_u32_e32 v4, v12, v4
	v_lshl_or_b32 v4, v4, 8, v1
	v_lshlrev_b64 v[12:13], 6, v[4:5]
	v_lshl_add_u64 v[28:29], s[8:9], 0, v[12:13]
	global_load_dwordx4 v[48:51], v[28:29], off
	global_load_dwordx4 v[52:55], v[28:29], off offset:16
	global_load_dwordx4 v[56:59], v[28:29], off offset:32
	global_load_dwordx4 v[60:63], v[28:29], off offset:48
	v_lshl_add_u64 v[2:3], v[2:3], 0, s[4:5]
	v_ashrrev_i32_e32 v4, 31, v2
	v_lshrrev_b32_e32 v4, 29, v4
	v_add_u32_e32 v4, v2, v4
	v_ashrrev_i32_e32 v11, 3, v4
	v_and_b32_e32 v4, -8, v4
	v_sub_u32_e32 v4, v2, v4
	v_cmp_gt_i32_e32 vcc, 0, v4
	s_nop 1
	v_cndmask_b32_e32 v12, v9, v10, vcc
	v_mul_lo_u32 v4, v4, v12
	v_add_u32_e32 v4, v4, v11
	v_ashrrev_i32_e32 v11, 31, v4
	v_lshrrev_b32_e32 v11, 25, v11
	v_add_u32_e32 v11, v4, v11
	v_ashrrev_i32_e32 v12, 7, v11
	v_lshlrev_b32_e32 v12, 3, v12
	v_sub_u32_e32 v13, 0xc0, v12
	v_min_i32_e32 v13, 8, v13
	v_sub_u32_e32 v14, 0, v13
	v_max_i32_e32 v13, v13, v14
	v_cvt_f32_u32_e32 v14, v13
	v_and_b32_e32 v11, 0xffffff80, v11
	v_sub_u32_e32 v4, v4, v11
	v_sub_u32_e32 v15, 0, v4
	v_rcp_iflag_f32_e32 v14, v14
	v_ashrrev_i32_e32 v11, 31, v4
	v_max_i32_e32 v4, v4, v15
;     __device__ __forceinline__ int pm_at(int i) const {
;         if (i >= R) return -1;
;         const long L = (long)(rev ? R - 1 - i : i) * G + c; if (L >= nwg) return -1;
;         int wgid = (int)L; { const int q = nwg / NXCD, r = nwg % NXCD, xcd = wgid % NXCD, off = wgid / NXCD; wgid = (xcd < r ? xcd * (q + 1) : r * (q + 1) + (xcd - r) * q) + off; }
;         const int nig = WGM * nN, gid = wgid / nig, fm = gid * WGM, gsz = (nM - fm) < WGM ? (nM - fm) : WGM;
;         return fm + ((wgid % nig) % gsz);
;     }
; __global__ void __launch_bounds__(NWAVES * 64, 2) mega_fwd(Args args) {
;     ...
;         { const int rowi = F.tid & 255;
;           for (int i = F.tid >> 8; i < pg8::UP_TAB_ROUNDS; i += 2) { const int pm = S.pm_at(i); if (pm < 0) break;
;               const f32x4* p = (const f32x4*)(F.stats + (size_t)(pm * 256 + rowi) * 16); const f32x4 a = p[0], b = p[1], c = p[2], d = p[3];
	v_sub_u32_e32 v15, 0, v13
	v_mul_f32_e32 v14, 0x4f7ffffe, v14
	v_cvt_u32_f32_e32 v14, v14
	v_mul_lo_u32 v15, v15, v14
	v_mul_hi_u32 v15, v14, v15
	v_add_u32_e32 v14, v14, v15
	v_mul_hi_u32 v14, v4, v14
	v_mul_lo_u32 v14, v14, v13
	v_sub_u32_e32 v4, v4, v14
	v_sub_u32_e32 v14, v4, v13
	v_cmp_ge_u32_e32 vcc, v4, v13
	s_nop 1
	v_cndmask_b32_e32 v4, v4, v14, vcc
	v_sub_u32_e32 v14, v4, v13
	v_cmp_ge_u32_e32 vcc, v4, v13
	s_nop 1
	v_cndmask_b32_e32 v4, v4, v14, vcc
	v_xor_b32_e32 v4, v4, v11
	v_sub_u32_e32 v4, v4, v11
	v_add_u32_e32 v4, v12, v4
	v_lshl_or_b32 v4, v4, 8, v1
	v_lshlrev_b64 v[12:13], 6, v[4:5]
	v_lshl_add_u64 v[28:29], s[8:9], 0, v[12:13]
	global_load_dwordx4 v[64:67], v[28:29], off
	global_load_dwordx4 v[68:71], v[28:29], off offset:16
	global_load_dwordx4 v[72:75], v[28:29], off offset:32
	global_load_dwordx4 v[76:79], v[28:29], off offset:48
	v_lshl_add_u64 v[2:3], v[2:3], 0, s[4:5]
	v_ashrrev_i32_e32 v4, 31, v2
	v_lshrrev_b32_e32 v4, 29, v4
	v_add_u32_e32 v4, v2, v4
	v_ashrrev_i32_e32 v11, 3, v4
	v_and_b32_e32 v4, -8, v4
	v_sub_u32_e32 v4, v2, v4
	v_cmp_gt_i32_e32 vcc, 0, v4
	s_nop 1
	v_cndmask_b32_e32 v12, v9, v10, vcc
	v_mul_lo_u32 v4, v4, v12
	v_add_u32_e32 v4, v4, v11
	v_ashrrev_i32_e32 v11, 31, v4
	v_lshrrev_b32_e32 v11, 25, v11
	v_add_u32_e32 v11, v4, v11
	v_ashrrev_i32_e32 v12, 7, v11
	v_lshlrev_b32_e32 v12, 3, v12
	v_sub_u32_e32 v13, 0xc0, v12
	v_min_i32_e32 v13, 8, v13
	v_sub_u32_e32 v14, 0, v13
	v_max_i32_e32 v13, v13, v14
	v_cvt_f32_u32_e32 v14, v13
	v_and_b32_e32 v11, 0xffffff80, v11
	v_sub_u32_e32 v4, v4, v11
	v_sub_u32_e32 v15, 0, v4
	v_rcp_iflag_f32_e32 v14, v14
	v_ashrrev_i32_e32 v11, 31, v4
	v_max_i32_e32 v4, v4, v15
	v_sub_u32_e32 v15, 0, v13
	v_mul_f32_e32 v14, 0x4f7ffffe, v14
	v_cvt_u32_f32_e32 v14, v14
	v_mul_lo_u32 v15, v15, v14
	v_mul_hi_u32 v15, v14, v15
	v_add_u32_e32 v14, v14, v15
	v_mul_hi_u32 v14, v4, v14
	v_mul_lo_u32 v14, v14, v13
	v_sub_u32_e32 v4, v4, v14
	v_sub_u32_e32 v14, v4, v13
	v_cmp_ge_u32_e32 vcc, v4, v13
	s_nop 1
	v_cndmask_b32_e32 v4, v4, v14, vcc
	v_sub_u32_e32 v14, v4, v13
	v_cmp_ge_u32_e32 vcc, v4, v13
	s_nop 1
	v_cndmask_b32_e32 v4, v4, v14, vcc
	v_xor_b32_e32 v4, v4, v11
	v_sub_u32_e32 v4, v4, v11
	v_add_u32_e32 v4, v12, v4
	v_lshl_or_b32 v4, v4, 8, v1
	v_lshlrev_b64 v[12:13], 6, v[4:5]
	v_lshl_add_u64 v[28:29], s[8:9], 0, v[12:13]
	global_load_dwordx4 v[80:83], v[28:29], off
	global_load_dwordx4 v[84:87], v[28:29], off offset:16
	global_load_dwordx4 v[88:91], v[28:29], off offset:32
	global_load_dwordx4 v[92:95], v[28:29], off offset:48
	v_lshl_add_u64 v[2:3], v[2:3], 0, s[4:5]
	v_ashrrev_i32_e32 v4, 31, v2
	v_lshrrev_b32_e32 v4, 29, v4
	v_add_u32_e32 v4, v2, v4
	v_ashrrev_i32_e32 v11, 3, v4
	v_and_b32_e32 v4, -8, v4
	v_sub_u32_e32 v4, v2, v4
	v_cmp_gt_i32_e32 vcc, 0, v4
	s_nop 1
	v_cndmask_b32_e32 v12, v9, v10, vcc
	v_mul_lo_u32 v4, v4, v12
	v_add_u32_e32 v4, v4, v11
	v_ashrrev_i32_e32 v11, 31, v4
	v_lshrrev_b32_e32 v11, 25, v11
	v_add_u32_e32 v11, v4, v11
	v_ashrrev_i32_e32 v12, 7, v11
	v_lshlrev_b32_e32 v12, 3, v12
	v_sub_u32_e32 v13, 0xc0, v12
	v_min_i32_e32 v13, 8, v13
	v_sub_u32_e32 v14, 0, v13
	v_max_i32_e32 v13, v13, v14
	v_cvt_f32_u32_e32 v14, v13
	v_and_b32_e32 v11, 0xffffff80, v11
	v_sub_u32_e32 v4, v4, v11
	v_sub_u32_e32 v15, 0, v4
	v_rcp_iflag_f32_e32 v14, v14
	v_ashrrev_i32_e32 v11, 31, v4
	v_max_i32_e32 v4, v4, v15
	v_sub_u32_e32 v15, 0, v13
	v_mul_f32_e32 v14, 0x4f7ffffe, v14
	v_cvt_u32_f32_e32 v14, v14
	v_mul_lo_u32 v15, v15, v14
	v_mul_hi_u32 v15, v14, v15
	v_add_u32_e32 v14, v14, v15
	v_mul_hi_u32 v14, v4, v14
	v_mul_lo_u32 v14, v14, v13
	v_sub_u32_e32 v4, v4, v14
	v_sub_u32_e32 v14, v4, v13
	v_cmp_ge_u32_e32 vcc, v4, v13
	s_nop 1
	v_cndmask_b32_e32 v4, v4, v14, vcc
	v_sub_u32_e32 v14, v4, v13
	v_cmp_ge_u32_e32 vcc, v4, v13
	s_nop 1
	v_cndmask_b32_e32 v4, v4, v14, vcc
	v_xor_b32_e32 v4, v4, v11
	v_sub_u32_e32 v4, v4, v11
	v_add_u32_e32 v4, v12, v4
	v_lshl_or_b32 v4, v4, 8, v1
	v_lshlrev_b64 v[12:13], 6, v[4:5]
	v_lshl_add_u64 v[28:29], s[8:9], 0, v[12:13]
	global_load_dwordx4 v[96:99], v[28:29], off
	global_load_dwordx4 v[100:103], v[28:29], off offset:16
	global_load_dwordx4 v[104:107], v[28:29], off offset:32
	global_load_dwordx4 v[108:111], v[28:29], off offset:48
	v_lshl_add_u64 v[2:3], v[2:3], 0, s[4:5]
	v_ashrrev_i32_e32 v4, 31, v2
	v_lshrrev_b32_e32 v4, 29, v4
	v_add_u32_e32 v4, v2, v4
	v_ashrrev_i32_e32 v11, 3, v4
	v_and_b32_e32 v4, -8, v4
	v_sub_u32_e32 v4, v2, v4
	v_cmp_gt_i32_e32 vcc, 0, v4
	s_nop 1
	v_cndmask_b32_e32 v12, v9, v10, vcc
	v_mul_lo_u32 v4, v4, v12
	v_add_u32_e32 v4, v4, v11
	v_ashrrev_i32_e32 v11, 31, v4
	v_lshrrev_b32_e32 v11, 25, v11
	v_add_u32_e32 v11, v4, v11
	v_ashrrev_i32_e32 v12, 7, v11
	v_lshlrev_b32_e32 v12, 3, v12
	v_sub_u32_e32 v13, 0xc0, v12
	v_min_i32_e32 v13, 8, v13
	v_sub_u32_e32 v14, 0, v13
	v_max_i32_e32 v13, v13, v14
	v_cvt_f32_u32_e32 v14, v13
	v_and_b32_e32 v11, 0xffffff80, v11
	v_sub_u32_e32 v4, v4, v11
	v_sub_u32_e32 v15, 0, v4
	v_rcp_iflag_f32_e32 v14, v14
	v_ashrrev_i32_e32 v11, 31, v4
	v_max_i32_e32 v4, v4, v15
	v_sub_u32_e32 v15, 0, v13
	v_mul_f32_e32 v14, 0x4f7ffffe, v14
	v_cvt_u32_f32_e32 v14, v14
	v_mul_lo_u32 v15, v15, v14
	v_mul_hi_u32 v15, v14, v15
	v_add_u32_e32 v14, v14, v15
	v_mul_hi_u32 v14, v4, v14
	v_mul_lo_u32 v14, v14, v13
	v_sub_u32_e32 v4, v4, v14
	v_sub_u32_e32 v14, v4, v13
	v_cmp_ge_u32_e32 vcc, v4, v13
	s_nop 1
	v_cndmask_b32_e32 v4, v4, v14, vcc
	v_sub_u32_e32 v14, v4, v13
	v_cmp_ge_u32_e32 vcc, v4, v13
	s_nop 1
	v_cndmask_b32_e32 v4, v4, v14, vcc
	v_xor_b32_e32 v4, v4, v11
	v_sub_u32_e32 v4, v4, v11
	v_add_u32_e32 v4, v12, v4
	v_lshl_or_b32 v4, v4, 8, v1
	v_lshlrev_b64 v[12:13], 6, v[4:5]
	v_lshl_add_u64 v[28:29], s[8:9], 0, v[12:13]
	global_load_dwordx4 v[112:115], v[28:29], off
	global_load_dwordx4 v[116:119], v[28:29], off offset:16
	global_load_dwordx4 v[120:123], v[28:29], off offset:32
	global_load_dwordx4 v[124:127], v[28:29], off offset:48
	v_lshl_add_u64 v[2:3], v[2:3], 0, s[4:5]
	s_waitcnt vmcnt(20)
; __global__ void __launch_bounds__(NWAVES * 64, 2) mega_fwd(Args args) {
;     ...
;               const f32x4* p = (const f32x4*)(F.stats + (size_t)(pm * 256 + rowi) * 16); const f32x4 a = p[0], b = p[1], c = p[2], d = p[3];
;               const float ssum = ((a[0] + a[1]) + (a[2] + a[3])) + ((b[0] + b[1]) + (b[2] + b[3])) + ((c[0] + c[1]) + (c[2] + c[3])) + ((d[0] + d[1]) + (d[2] + d[3]));
;               tab[i * 256 + rowi] = __builtin_amdgcn_rsqf(ssum * (1.0f / 1024.0f) + EPS); }
;           __syncthreads(); }
	v_mov_b32_e32 v28, v33
	v_mov_b32_e32 v29, v34
	v_mov_b32_e32 v33, v35
	v_mov_b32_e32 v34, v37
	v_mov_b32_e32 v35, v38
	v_mov_b32_e32 v37, v39
	v_pk_add_f32 v[32:33], v[28:29], v[32:33]
	v_pk_add_f32 v[34:35], v[34:35], v[36:37]
	v_pk_add_f32 v[32:33], v[32:33], v[32:33] op_sel:[0,1] op_sel_hi:[1,0]
	v_pk_add_f32 v[34:35], v[34:35], v[34:35] op_sel:[0,1] op_sel_hi:[1,0]
	v_add_f32_e32 v38, v40, v41
	v_add_f32_e32 v40, v42, v43
	v_mov_b32_e32 v39, v46
	v_mov_b32_e32 v41, v47
	v_mov_b32_e32 v33, v44
	v_mov_b32_e32 v35, v45
	v_pk_add_f32 v[36:37], v[38:39], v[40:41]
	v_pk_add_f32 v[32:33], v[32:33], v[34:35]
	s_nop 0
	v_pk_add_f32 v[32:33], v[32:33], v[36:37]
	s_nop 0
	v_add_f32_e32 v11, v32, v33
	v_fmamk_f32 v11, v11, 0x3a800000, v8
	v_rsq_f32_e32 v11, v11
	ds_write_b32 v7, v11
	v_add_u32_e32 v7, 0x800, v7
	s_waitcnt vmcnt(16)
	v_mov_b32_e32 v28, v49
	v_mov_b32_e32 v29, v50
	v_mov_b32_e32 v49, v51
	v_mov_b32_e32 v50, v53
	v_mov_b32_e32 v51, v54
	v_mov_b32_e32 v53, v55
	v_pk_add_f32 v[48:49], v[28:29], v[48:49]
	v_pk_add_f32 v[50:51], v[50:51], v[52:53]
	v_pk_add_f32 v[48:49], v[48:49], v[48:49] op_sel:[0,1] op_sel_hi:[1,0]
	v_pk_add_f32 v[50:51], v[50:51], v[50:51] op_sel:[0,1] op_sel_hi:[1,0]
	v_add_f32_e32 v54, v56, v57
	v_add_f32_e32 v56, v58, v59
	v_mov_b32_e32 v55, v62
	v_mov_b32_e32 v57, v63
	v_mov_b32_e32 v49, v60
	v_mov_b32_e32 v51, v61
	v_pk_add_f32 v[52:53], v[54:55], v[56:57]
	v_pk_add_f32 v[48:49], v[48:49], v[50:51]
	s_nop 0
	v_pk_add_f32 v[48:49], v[48:49], v[52:53]
	s_nop 0
	v_add_f32_e32 v11, v48, v49
	v_fmamk_f32 v11, v11, 0x3a800000, v8
	v_rsq_f32_e32 v11, v11
	ds_write_b32 v7, v11
	v_add_u32_e32 v7, 0x800, v7
	s_waitcnt vmcnt(12)
	v_mov_b32_e32 v28, v65
	v_mov_b32_e32 v29, v66
	v_mov_b32_e32 v65, v67
	v_mov_b32_e32 v66, v69
	v_mov_b32_e32 v67, v70
	v_mov_b32_e32 v69, v71
	v_pk_add_f32 v[64:65], v[28:29], v[64:65]
	v_pk_add_f32 v[66:67], v[66:67], v[68:69]
	v_pk_add_f32 v[64:65], v[64:65], v[64:65] op_sel:[0,1] op_sel_hi:[1,0]
	v_pk_add_f32 v[66:67], v[66:67], v[66:67] op_sel:[0,1] op_sel_hi:[1,0]
	v_add_f32_e32 v70, v72, v73
	v_add_f32_e32 v72, v74, v75
	v_mov_b32_e32 v71, v78
	v_mov_b32_e32 v73, v79
	v_mov_b32_e32 v65, v76
	v_mov_b32_e32 v67, v77
	v_pk_add_f32 v[68:69], v[70:71], v[72:73]
	v_pk_add_f32 v[64:65], v[64:65], v[66:67]
	s_nop 0
	v_pk_add_f32 v[64:65], v[64:65], v[68:69]
	s_nop 0
	v_add_f32_e32 v11, v64, v65
	v_fmamk_f32 v11, v11, 0x3a800000, v8
	v_rsq_f32_e32 v11, v11
	ds_write_b32 v7, v11
	v_add_u32_e32 v7, 0x800, v7
	s_waitcnt vmcnt(8)
	v_mov_b32_e32 v28, v81
	v_mov_b32_e32 v29, v82
	v_mov_b32_e32 v81, v83
	v_mov_b32_e32 v82, v85
	v_mov_b32_e32 v83, v86
	v_mov_b32_e32 v85, v87
	v_pk_add_f32 v[80:81], v[28:29], v[80:81]
	v_pk_add_f32 v[82:83], v[82:83], v[84:85]
	v_pk_add_f32 v[80:81], v[80:81], v[80:81] op_sel:[0,1] op_sel_hi:[1,0]
	v_pk_add_f32 v[82:83], v[82:83], v[82:83] op_sel:[0,1] op_sel_hi:[1,0]
	v_add_f32_e32 v86, v88, v89
	v_add_f32_e32 v88, v90, v91
	v_mov_b32_e32 v87, v94
	v_mov_b32_e32 v89, v95
	v_mov_b32_e32 v81, v92
	v_mov_b32_e32 v83, v93
	v_pk_add_f32 v[84:85], v[86:87], v[88:89]
	v_pk_add_f32 v[80:81], v[80:81], v[82:83]
	s_nop 0
	v_pk_add_f32 v[80:81], v[80:81], v[84:85]
	s_nop 0
	v_add_f32_e32 v11, v80, v81
	v_fmamk_f32 v11, v11, 0x3a800000, v8
	v_rsq_f32_e32 v11, v11
	ds_write_b32 v7, v11
	v_add_u32_e32 v7, 0x800, v7
	s_waitcnt vmcnt(4)
	v_mov_b32_e32 v28, v97
	v_mov_b32_e32 v29, v98
	v_mov_b32_e32 v97, v99
	v_mov_b32_e32 v98, v101
	v_mov_b32_e32 v99, v102
	v_mov_b32_e32 v101, v103
	v_pk_add_f32 v[96:97], v[28:29], v[96:97]
	v_pk_add_f32 v[98:99], v[98:99], v[100:101]
	v_pk_add_f32 v[96:97], v[96:97], v[96:97] op_sel:[0,1] op_sel_hi:[1,0]
	v_pk_add_f32 v[98:99], v[98:99], v[98:99] op_sel:[0,1] op_sel_hi:[1,0]
	v_add_f32_e32 v102, v104, v105
	v_add_f32_e32 v104, v106, v107
	v_mov_b32_e32 v103, v110
	v_mov_b32_e32 v105, v111
	v_mov_b32_e32 v97, v108
	v_mov_b32_e32 v99, v109
	v_pk_add_f32 v[100:101], v[102:103], v[104:105]
	v_pk_add_f32 v[96:97], v[96:97], v[98:99]
	s_nop 0
	v_pk_add_f32 v[96:97], v[96:97], v[100:101]
	s_nop 0
	v_add_f32_e32 v11, v96, v97
	v_fmamk_f32 v11, v11, 0x3a800000, v8
	v_rsq_f32_e32 v11, v11
	ds_write_b32 v7, v11
	v_add_u32_e32 v7, 0x800, v7
	s_waitcnt vmcnt(0)
	v_mov_b32_e32 v28, v113
	v_mov_b32_e32 v29, v114
	v_mov_b32_e32 v113, v115
	v_mov_b32_e32 v114, v117
	v_mov_b32_e32 v115, v118
	v_mov_b32_e32 v117, v119
	v_pk_add_f32 v[112:113], v[28:29], v[112:113]
	v_pk_add_f32 v[114:115], v[114:115], v[116:117]
	v_pk_add_f32 v[112:113], v[112:113], v[112:113] op_sel:[0,1] op_sel_hi:[1,0]
	v_pk_add_f32 v[114:115], v[114:115], v[114:115] op_sel:[0,1] op_sel_hi:[1,0]
	v_add_f32_e32 v118, v120, v121
	v_add_f32_e32 v120, v122, v123
	v_mov_b32_e32 v119, v126
	v_mov_b32_e32 v121, v127
	v_mov_b32_e32 v113, v124
	v_mov_b32_e32 v115, v125
	v_pk_add_f32 v[116:117], v[118:119], v[120:121]
	v_pk_add_f32 v[112:113], v[112:113], v[114:115]
	s_nop 0
	v_pk_add_f32 v[112:113], v[112:113], v[116:117]
	s_nop 0
	v_add_f32_e32 v11, v112, v113
	v_fmamk_f32 v11, v11, 0x3a800000, v8
	v_rsq_f32_e32 v11, v11
	ds_write_b32 v7, v11
	v_add_u32_e32 v7, 0x800, v7
	s_branch .LBB0_1367
.Ltab_slow:
	s_branch .LBB0_1361
.LBB0_1360:
	s_or_b64 exec, exec, s[12:13]
	s_and_b64 s[0:1], exec, s[14:15]
	s_or_b64 s[6:7], s[0:1], s[6:7]
	s_andn2_b64 exec, exec, s[6:7]
	s_cbranch_execz .LBB0_1367
